# q/kv phase rebalanced: every workgroup takes kv units 2bx,2bx+1 (5 vs 3 epilogues instead of 6 vs 2)
# speedup vs baseline: 1.0150x; 1.0009x over previous
.LBB0_400:
	s_cbranch_execz .LBB0_406
	s_mov_b64 s[4:5], -1
	s_and_b64 vcc, exec, s[8:9]
	s_cbranch_vccz .LBB0_403
	s_mul_i32 s0, s96, 3
	s_add_i32 s1, s0, 0xfffffe80
	s_mul_hi_u32 s2, s1, 0xaaaaaaab
	s_lshr_b32 s2, s2, 2
	s_mul_i32 s3, s2, 6
	s_sub_i32 s1, s1, s3
	v_mov_b32_e32 v3, s1
	v_mov_b32_e32 v4, s1
	s_add_i32 s1, 0, 0x22500
	v_mov_b32_e32 v1, s1
	s_add_i32 s1, s0, 0xfffffe81
	v_mov_b32_e32 v2, s2
	s_mul_hi_u32 s2, s1, 0xaaaaaaab
	s_lshr_b32 s2, s2, 2
	s_mul_i32 s3, s2, 6
	s_sub_i32 s1, s1, s3
	ds_write_b96 v1, v[2:4]
	v_mov_b32_e32 v3, s1
	v_mov_b32_e32 v4, s1
	s_add_i32 s1, 0, 0x22510
	v_mov_b32_e32 v1, s1
	s_add_i32 s1, s0, 0xfffffe82
	v_mov_b32_e32 v2, s2
	s_mul_hi_u32 s2, s1, 0xaaaaaaab
	s_lshr_b32 s2, s2, 2
	s_mul_i32 s3, s2, 6
	s_sub_i32 s1, s1, s3
	ds_write_b96 v1, v[2:4]
	v_mov_b32_e32 v3, s1
	v_mov_b32_e32 v4, s1
	s_add_i32 s1, 0, 0x22520
	v_mov_b32_e32 v1, s1
	v_mov_b32_e32 v2, s2
	ds_write_b96 v1, v[2:4]
	s_lshl_b32 s0, s96, 1
	s_lshr_b32 s1, s0, 3
	s_and_b32 s2, s0, 7
	v_mov_b32_e32 v2, s1
	v_mov_b32_e32 v3, s2
	v_mov_b32_e32 v4, s2
	s_add_i32 s1, 0, 0x22600
	v_mov_b32_e32 v1, s1
	ds_write_b96 v1, v[2:4]
	s_or_b32 s2, s2, 1
	v_mov_b32_e32 v3, s2
	v_mov_b32_e32 v4, s2
	s_add_i32 s1, 0, 0x22610
	v_mov_b32_e32 v1, s1
	ds_write_b96 v1, v[2:4]
	s_mov_b64 s[4:5], 0
.LBB0_403:
	s_andn2_b64 vcc, exec, s[4:5]
	s_mov_b32 s0, 1
	s_cbranch_vccnz .LBB0_405
	s_ashr_i32 s1, s96, 1
	s_and_b32 s2, s96, 1
	s_or_b32 s2, s2, 8
	v_mov_b32_e32 v2, s1
	s_add_i32 s1, 0, 0x22400
	v_mov_b32_e32 v3, s2
	v_mov_b32_e32 v4, s2
	v_mov_b32_e32 v1, s1
	ds_write_b96 v1, v[2:4]
	s_lshl_b32 s3, s96, 1
	s_lshr_b32 s1, s3, 3
	s_and_b32 s3, s3, 7
	v_mov_b32_e32 v2, s1
	s_add_i32 s1, 0, 0x22600
	v_mov_b32_e32 v3, s3
	v_mov_b32_e32 v4, s3
	v_mov_b32_e32 v1, s1
	ds_write_b96 v1, v[2:4]
	s_or_b32 s3, s3, 1
	v_mov_b32_e32 v3, s3
	v_mov_b32_e32 v4, s3
	s_add_i32 s1, 0, 0x22610
	v_mov_b32_e32 v1, s1
	ds_write_b96 v1, v[2:4]
	s_mov_b32 s2, 0
	s_mov_b32 s3, 2
	s_branch .LBB0_406
.LBB0_405:
	s_mov_b32 s0, 0
	s_mov_b32 s2, 3
	s_mov_b32 s3, 2
